# v8 + LayerNorm butterfly all-reduces through DPP and permlane swaps instead of ds_bpermute (bit-identical sums)
# speedup vs baseline: 1.0043x; 1.0043x over previous
; DI void wave_sum2(float& a, float& b) {
; #pragma unroll
;     for (int o = 1; o < 64; o <<= 1) { const float ta = __shfl_xor(a, o), tb = __shfl_xor(b, o); a += ta; b += tb; }
; }
; DI void lnmod_phase(const Args& A, LAS unsigned char* lds, int tid, int bid, int G, bool init, int l_norm, int i_norm, int l_mod, int i_mod, bool want_dt, int nrows, bool ctx_partial, const float* gprev, const float* bprev) {
;     ...
;             float s = 0.f, s2 = 0.f;
; #pragma unroll
;             for (int j = 0; j < 4; ++j) { s += (v[j].x + v[j].y) + (v[j].z + v[j].w); s2 += (v[j].x * v[j].x + v[j].y * v[j].y) + (v[j].z * v[j].z + v[j].w * v[j].w); }
;             wave_sum2(s, s2);
;             const float mean = s * (1.f / DM);
;             const float rstd = 1.0f / sqrtf(fmaxf(s2 * (1.f / DM) - mean * mean, 0.f) + 1e-5f);
; #pragma unroll
;             for (int j = 0; j < 4; ++j) v[j] = v[j] - mean;
;             if (l_mod >= 0 && lane == 0) STAT[row] = (f32x2){mean, rstd};
.LBB0_209:
	s_or_b64 exec, exec, s[6:7]
	s_andn2_b64 vcc, exec, s[8:9]
	s_cbranch_vccnz .LBB0_204
	v_pk_add_f32 v[110:111], v[106:107], v[90:91]
	v_mul_f32_e32 v99, v91, v91
	v_add_f32_e32 v87, v110, v111
	v_add_f32_e32 v109, 0, v87
	v_mul_f32_e32 v87, v106, v106
	v_fmac_f32_e32 v87, v90, v90
	v_fmac_f32_e32 v99, v107, v107
	v_add_f32_e32 v87, v87, v99
	v_mul_f32_e32 v99, v102, v102
	v_mul_f32_e32 v101, v93, v93
	v_pk_add_f32 v[110:111], v[102:103], v[92:93]
	v_fmac_f32_e32 v99, v92, v92
	v_fmac_f32_e32 v101, v103, v103
	v_pk_add_f32 v[110:111], v[110:111], v[110:111] op_sel_hi:[0,1]
	v_add_f32_e32 v99, v99, v101
	v_add_f32_e32 v87, v87, v99
	v_mul_f32_e32 v99, v97, v97
	v_mul_f32_e32 v110, v95, v95
	v_add_f32_e32 v101, v96, v97
	v_add_f32_e32 v105, v94, v95
	v_fmac_f32_e32 v99, v96, v96
	v_fmac_f32_e32 v110, v94, v94
	v_add_f32_e32 v99, v99, v110
	v_pk_add_f32 v[112:113], v[100:101], v[104:105]
	v_mul_f32_e32 v101, v104, v104
	v_mul_f32_e32 v105, v108, v108
	v_add_f32_e32 v87, v99, v87
	v_mov_b32_e32 v99, v111
	v_fmac_f32_e32 v101, v100, v100
	v_fmac_f32_e32 v105, v98, v98
	v_pk_add_f32 v[110:111], v[98:99], v[108:109]
	v_add_f32_e32 v101, v101, v105
	v_pk_add_f32 v[110:111], v[112:113], v[110:111]
	v_add_f32_e32 v87, v101, v87
	v_and_b32_e32 v101, 64, v210
	v_add_f32_e32 v99, v110, v111
	v_add_u32_e32 v110, 64, v101
	v_xor_b32_e32 v101, 1, v210
	v_cmp_lt_i32_e32 vcc, v101, v110
	s_mov_b32 s6, 0x3a800000
	s_nop 0
	v_cndmask_b32_e32 v101, v210, v101, vcc
	v_lshlrev_b32_e32 v114, 2, v101
	s_nop 1
	v_mov_b32_dpp v101, v99 quad_perm:[1,0,3,2] row_mask:0xf bank_mask:0xf
	v_mov_b32_dpp v105, v87 quad_perm:[1,0,3,2] row_mask:0xf bank_mask:0xf
	s_waitcnt lgkmcnt(1)
	v_add_f32_e32 v99, v99, v101
	v_xor_b32_e32 v101, 2, v210
	v_cmp_lt_i32_e32 vcc, v101, v110
	s_waitcnt lgkmcnt(0)
	v_add_f32_e32 v87, v87, v105
	v_cndmask_b32_e32 v101, v210, v101, vcc
	v_lshlrev_b32_e32 v111, 2, v101
	s_nop 1
	v_mov_b32_dpp v101, v99 quad_perm:[2,3,0,1] row_mask:0xf bank_mask:0xf
	v_mov_b32_dpp v105, v87 quad_perm:[2,3,0,1] row_mask:0xf bank_mask:0xf
	s_waitcnt lgkmcnt(1)
	v_add_f32_e32 v99, v99, v101
	v_xor_b32_e32 v101, 4, v210
	v_cmp_lt_i32_e32 vcc, v101, v110
	s_waitcnt lgkmcnt(0)
	v_add_f32_e32 v87, v87, v105
	v_cndmask_b32_e32 v101, v210, v101, vcc
	v_lshlrev_b32_e32 v109, 2, v101
	s_nop 1
	v_mov_b32_dpp v101, v99 row_half_mirror row_mask:0xf bank_mask:0xf
	v_mov_b32_dpp v105, v87 row_half_mirror row_mask:0xf bank_mask:0xf
	s_waitcnt lgkmcnt(1)
	v_add_f32_e32 v99, v99, v101
	v_xor_b32_e32 v101, 8, v210
	v_cmp_lt_i32_e32 vcc, v101, v110
	s_waitcnt lgkmcnt(0)
	v_add_f32_e32 v87, v87, v105
	v_cndmask_b32_e32 v101, v210, v101, vcc
	v_lshlrev_b32_e32 v105, 2, v101
	s_nop 1
	v_mov_b32_dpp v101, v99 row_mirror row_mask:0xf bank_mask:0xf
	v_mov_b32_dpp v112, v87 row_mirror row_mask:0xf bank_mask:0xf
	s_waitcnt lgkmcnt(1)
	v_add_f32_e32 v99, v99, v101
	v_xor_b32_e32 v101, 16, v210
	v_cmp_lt_i32_e32 vcc, v101, v110
	s_waitcnt lgkmcnt(0)
	v_add_f32_e32 v87, v87, v112
	v_cndmask_b32_e32 v101, v210, v101, vcc
	v_lshlrev_b32_e32 v101, 2, v101
	v_mov_b32_e32 v112, v99
	v_mov_b32_e32 v113, v87
	s_nop 1
	v_permlane16_swap_b32_e32 v99, v112
	v_permlane16_swap_b32_e32 v87, v113
	s_waitcnt lgkmcnt(1)
	v_add_f32_e32 v112, v99, v112
	v_xor_b32_e32 v99, 32, v210
	v_cmp_lt_i32_e32 vcc, v99, v110
	s_waitcnt lgkmcnt(0)
	v_add_f32_e32 v87, v87, v113
	v_cndmask_b32_e32 v99, v210, v99, vcc
	v_lshlrev_b32_e32 v99, 2, v99
	v_mov_b32_e32 v110, v112
	v_mov_b32_e32 v113, v87
	s_nop 1
	v_permlane32_swap_b32_e32 v112, v110
	v_permlane32_swap_b32_e32 v87, v113
	s_waitcnt lgkmcnt(1)
	v_add_f32_e32 v110, v112, v110
	v_mul_f32_e32 v112, 0x3a800000, v110
	s_waitcnt lgkmcnt(0)
	v_add_f32_e32 v87, v87, v113
	v_mul_f32_e32 v110, v112, v112
	v_fma_f32 v87, v87, s6, -v110
	v_max_f32_e32 v87, 0, v87
	v_add_f32_e32 v87, 0x3727c5ac, v87
	v_mul_f32_e32 v110, 0x4f800000, v87
	v_cmp_gt_f32_e32 vcc, s65, v87
	s_nop 1
	v_cndmask_b32_e32 v87, v87, v110, vcc
	v_sqrt_f32_e32 v110, v87
	s_nop 0
	v_add_u32_e32 v113, -1, v110
	v_fma_f32 v115, -v113, v110, v87
	v_cmp_ge_f32_e64 s[6:7], 0, v115
	v_add_u32_e32 v115, 1, v110
	s_nop 0
	v_cndmask_b32_e64 v113, v110, v113, s[6:7]
	v_fma_f32 v110, -v115, v110, v87
	v_cmp_lt_f32_e64 s[6:7], 0, v110
	s_nop 1
	v_cndmask_b32_e64 v110, v113, v115, s[6:7]
	v_mul_f32_e32 v113, 0x37800000, v110
	v_cndmask_b32_e32 v110, v110, v113, vcc
	v_cmp_class_f32_e32 vcc, v87, v208
	s_nop 1
	v_cndmask_b32_e32 v87, v110, v87, vcc
	v_div_scale_f32 v110, s[6:7], v87, v87, 1.0
	v_rcp_f32_e32 v113, v110
	s_nop 0
	v_fma_f32 v115, -v110, v113, 1.0
	v_fmac_f32_e32 v113, v115, v113
	v_div_scale_f32 v115, vcc, 1.0, v87, 1.0
	v_mul_f32_e32 v118, v115, v113
	v_fma_f32 v119, -v110, v118, v115
	v_fmac_f32_e32 v118, v119, v113
	v_fma_f32 v110, -v110, v118, v115
	v_div_fmas_f32 v110, v110, v113, v118
	v_div_fixup_f32 v110, v110, v87, 1.0
	s_and_saveexec_b64 s[6:7], s[20:21]
	s_cbranch_execz .LBB0_212
	v_readlane_b32 s36, v253, 23
	v_readlane_b32 s38, v253, 25
	v_readlane_b32 s39, v253, 26
	v_mov_b32_e32 v113, v110
	v_readlane_b32 s37, v253, 24
	v_lshl_add_u64 v[118:119], s[38:39], 0, v[74:75]
	global_store_dwordx2 v[118:119], v[112:113], off

; DI unsigned pk2(float lo, float hi) { f32x2 v = {lo, hi}; bf16x2_t b = __builtin_convertvector(v, bf16x2_t); return __builtin_bit_cast(unsigned, b); }
; DI void lnmod_phase(const Args& A, LAS unsigned char* lds, int tid, int bid, int G, bool init, int l_norm, int i_norm, int l_mod, int i_mod, bool want_dt, int nrows, bool ctx_partial, const float* gprev, const float* bprev) {
;     ...
;             for (int j = 0; j < 4; ++j) v[j] = v[j] - mean;
;             if (l_mod >= 0 && lane == 0) STAT[row] = (f32x2){mean, rstd};
; #pragma unroll
;             for (int j = 0; j < 4; ++j) v[j] = v[j] * rstd * g[j] + bb[j];
;         }
;         if (init && lane == 0) STAT[row] = (f32x2){0.f, 1.f};
;         if (init) {
; #pragma unroll
;             for (int j = 0; j < 4; ++j) { u32x2 w_; w_.x = pkh2(v[j].x, v[j].y); w_.y = pkh2(v[j].z, v[j].w); *(u32x2*)(xout + 256 * j + 4 * lane) = w_; }
;         }
;         if (l_norm >= 0 && l_mod < 0) {
; #pragma unroll
;             for (int j = 0; j < 4; ++j) *(f32x4*)(A.out + (size_t)row * DM + 256 * j + 4 * lane) = v[j];
;         }
;         if (l_mod >= 0) {
;             const int mi = row < M_LAT ? (row >> 12) : 8;
;             const float* mp = MOD + ((size_t)l_mod * 9 + mi) * 9216 + i_mod * 3072;
;             if (mi != mi_cur) { mi_cur = mi;
; #pragma unroll
;                 for (int j = 0; j < 4; ++j) { shv[j] = *(const f32x4*)(mp + 256 * j + 4 * lane); sclv[j] = *(const f32x4*)(mp + 1024 + 256 * j + 4 * lane) + 1.0f; } }
;             float d0 = 0.f, d1 = 0.f, d2 = 0.f, d3 = 0.f;
; #pragma unroll
;             for (int j = 0; j < 4; ++j) {
;                 const f32x4 a = v[j] * sclv[j] + shv[j];
;                 u32x2 w; w.x = pk2(a.x, a.y); w.y = pk2(a.z, a.w);
;                 *(u32x2*)(Abuf + (size_t)row * DM + 256 * j + 4 * lane) = w;
;                 if (want_dt) {
;                     const int k0 = 256 * j + 4 * lane;
;                     const f32x4 w0 = wdt[k0], w1 = wdt[k0 + 1], w2 = wdt[k0 + 2], w3 = wdt[k0 + 3];
;                     d0 += a.x * w0.x + a.y * w1.x + a.z * w2.x + a.w * w3.x;
;                     d1 += a.x * w0.y + a.y * w1.y + a.z * w2.y + a.w * w3.y;
;                     d2 += a.x * w0.z + a.y * w1.z + a.z * w2.z + a.w * w3.z;
;                     d3 += a.x * w0.w + a.y * w1.w + a.z * w2.w + a.w * w3.w;
;                 }
.LBB0_214:
	s_or_b64 exec, exec, s[6:7]
	v_sub_f32_e32 v87, v106, v112
	v_sub_f32_e32 v86, v90, v112
	v_sub_f32_e32 v91, v91, v112
	v_sub_f32_e32 v90, v107, v112
	v_sub_f32_e32 v106, v92, v112
	v_sub_f32_e32 v93, v93, v112
	v_sub_f32_e32 v92, v103, v112
	v_pk_mul_f32 v[90:91], v[90:91], v[110:111] op_sel_hi:[1,0]
	v_pk_mul_f32 v[86:87], v[86:87], v[110:111] op_sel_hi:[1,0]
	v_sub_f32_e32 v95, v95, v112
	v_sub_f32_e32 v94, v94, v112
	v_pk_fma_f32 v[118:119], v[12:13], v[86:87], v[28:29]
	v_pk_fma_f32 v[86:87], v[14:15], v[90:91], v[30:31]
	v_pk_mul_f32 v[90:91], v[92:93], v[110:111] op_sel_hi:[1,0]
	v_sub_f32_e32 v107, v102, v112
	v_sub_f32_e32 v97, v97, v112
	v_sub_f32_e32 v96, v96, v112
	v_sub_f32_e32 v103, v104, v112
	v_sub_f32_e32 v102, v100, v112
	v_sub_f32_e32 v113, v108, v112
	v_sub_f32_e32 v112, v98, v112
	v_pk_fma_f32 v[126:127], v[10:11], v[90:91], v[26:27]
	v_pk_mul_f32 v[90:91], v[94:95], v[110:111] op_sel_hi:[1,0]
	s_mov_b32 s6, 0x3800000
	v_pk_mul_f32 v[92:93], v[106:107], v[110:111] op_sel_hi:[1,0]
	v_pk_fma_f32 v[130:131], v[6:7], v[90:91], v[22:23]
	v_pk_mul_f32 v[90:91], v[112:113], v[110:111] op_sel_hi:[1,0]
	s_waitcnt vmcnt(3)
	v_pk_fma_f32 v[86:87], v[86:87], v[58:59], v[46:47]
	v_pk_fma_f32 v[128:129], v[118:119], v[56:57], v[44:45]
	v_add_co_u32_e32 v138, vcc, s6, v88
	v_pk_fma_f32 v[106:107], v[8:9], v[92:93], v[24:25]
	v_pk_mul_f32 v[92:93], v[96:97], v[110:111] op_sel_hi:[1,0]
	v_pk_fma_f32 v[112:113], v[2:3], v[90:91], v[18:19]
	v_cvt_pk_bf16_f32 v90, v128, v129
	v_cvt_pk_bf16_f32 v91, v86, v87
	v_addc_co_u32_e32 v139, vcc, 0, v89, vcc
	v_pk_fma_f32 v[96:97], v[4:5], v[92:93], v[20:21]
	v_pk_mul_f32 v[92:93], v[102:103], v[110:111] op_sel_hi:[1,0]
	global_store_dwordx2 v[138:139], v[90:91], off
	v_pk_fma_f32 v[102:103], v[0:1], v[92:93], v[16:17]
	ds_read_b128 v[88:91], v67
	ds_read_b128 v[92:95], v67 offset:16
	ds_read_b128 v[118:121], v67 offset:32
	ds_read_b128 v[122:125], v67 offset:48
	s_waitcnt vmcnt(3)
	v_pk_fma_f32 v[162:163], v[126:127], v[50:51], v[42:43]
	v_pk_fma_f32 v[106:107], v[106:107], v[48:49], v[40:41]
	s_waitcnt lgkmcnt(2)
	v_pk_mul_f32 v[92:93], v[128:129], v[92:93] op_sel:[1,0]
	s_waitcnt vmcnt(2)
	v_pk_fma_f32 v[166:167], v[130:131], v[54:55], v[38:39]
	v_pk_fma_f32 v[88:89], v[128:129], v[88:89], v[92:93] op_sel_hi:[0,1,1]
	s_waitcnt lgkmcnt(1)
	v_pk_fma_f32 v[142:143], v[86:87], v[118:119], v[88:89] op_sel_hi:[0,1,1]
	v_pk_mul_f32 v[88:89], v[128:129], v[94:95] op_sel:[1,0]
	v_pk_fma_f32 v[96:97], v[96:97], v[52:53], v[36:37]
	v_pk_fma_f32 v[88:89], v[128:129], v[90:91], v[88:89] op_sel_hi:[0,1,1]
	v_pk_fma_f32 v[150:151], v[86:87], v[120:121], v[88:89] op_sel_hi:[0,1,1]
	v_cvt_pk_bf16_f32 v88, v106, v107
	v_cvt_pk_bf16_f32 v89, v162, v163
	global_store_dwordx2 v[138:139], v[88:89], off offset:512
	ds_read_b128 v[88:91], v67 offset:4096
	ds_read_b128 v[92:95], v67 offset:4112
	ds_read_b128 v[118:121], v67 offset:4128
	ds_read_b128 v[126:129], v67 offset:4144
	s_waitcnt vmcnt(2)
	v_pk_fma_f32 v[112:113], v[112:113], v[62:63], v[34:35]
	v_pk_fma_f32 v[102:103], v[102:103], v[60:61], v[32:33]
	s_waitcnt lgkmcnt(2)
	v_pk_mul_f32 v[92:93], v[106:107], v[92:93] op_sel:[1,0]
	v_pk_fma_f32 v[122:123], v[86:87], v[122:123], v[142:143] op_sel:[1,0,0]
	v_pk_fma_f32 v[164:165], v[106:107], v[88:89], v[92:93] op_sel_hi:[0,1,1]
	v_pk_mul_f32 v[88:89], v[106:107], v[94:95] op_sel:[1,0]
	s_waitcnt lgkmcnt(1)
	v_pk_fma_f32 v[118:119], v[162:163], v[118:119], v[164:165] op_sel_hi:[0,1,1]
	v_pk_fma_f32 v[106:107], v[106:107], v[90:91], v[88:89] op_sel_hi:[0,1,1]
	v_cvt_pk_bf16_f32 v88, v96, v97
	v_cvt_pk_bf16_f32 v89, v166, v167
	global_store_dwordx2 v[138:139], v[88:89], off offset:1024
	ds_read_b128 v[88:91], v67 offset:8192
	ds_read_b128 v[92:95], v67 offset:8208
	ds_read_b128 v[130:133], v67 offset:8224
	ds_read_b128 v[134:137], v67 offset:8240
	v_pk_add_f32 v[122:123], v[122:123], 0 op_sel_hi:[1,0]
	s_waitcnt lgkmcnt(4)
	v_pk_fma_f32 v[118:119], v[162:163], v[126:127], v[118:119] op_sel:[1,0,0]
	s_waitcnt lgkmcnt(2)
	v_pk_mul_f32 v[168:169], v[96:97], v[92:93] op_sel:[1,0]
	v_cvt_pk_bf16_f32 v92, v102, v103
	v_cvt_pk_bf16_f32 v93, v112, v113
	global_store_dwordx2 v[138:139], v[92:93], off offset:1536
	v_pk_mul_f32 v[170:171], v[96:97], v[94:95] op_sel:[1,0]
	ds_read_b128 v[92:95], v67 offset:12288
	ds_read_b128 v[138:141], v67 offset:12304
	ds_read_b128 v[154:157], v67 offset:12320
	ds_read_b128 v[158:161], v67 offset:12336
	v_pk_fma_f32 v[88:89], v[96:97], v[88:89], v[168:169] op_sel_hi:[0,1,1]
	s_waitcnt lgkmcnt(5)
; DI unsigned pk2(float lo, float hi) { f32x2 v = {lo, hi}; bf16x2_t b = __builtin_convertvector(v, bf16x2_t); return __builtin_bit_cast(unsigned, b); }
; DI void wave_sum4(float& a, float& b, float& c, float& d) {
; #pragma unroll
;     for (int o = 1; o < 64; o <<= 1) { const float ta = __shfl_xor(a, o), tb = __shfl_xor(b, o), tc = __shfl_xor(c, o), td = __shfl_xor(d, o); a += ta; b += tb; c += tc; d += td; }
; }
; DI void lnmod_phase(const Args& A, LAS unsigned char* lds, int tid, int bid, int G, bool init, int l_norm, int i_norm, int l_mod, int i_mod, bool want_dt, int nrows, bool ctx_partial, const float* gprev, const float* bprev) {
;     ...
;             float d0 = 0.f, d1 = 0.f, d2 = 0.f, d3 = 0.f;
; #pragma unroll
;             for (int j = 0; j < 4; ++j) {
;                 const f32x4 a = v[j] * sclv[j] + shv[j];
;                 u32x2 w; w.x = pk2(a.x, a.y); w.y = pk2(a.z, a.w);
;                 *(u32x2*)(Abuf + (size_t)row * DM + 256 * j + 4 * lane) = w;
;                 if (want_dt) {
;                     const int k0 = 256 * j + 4 * lane;
;                     const f32x4 w0 = wdt[k0], w1 = wdt[k0 + 1], w2 = wdt[k0 + 2], w3 = wdt[k0 + 3];
;                     d0 += a.x * w0.x + a.y * w1.x + a.z * w2.x + a.w * w3.x;
;                     d1 += a.x * w0.y + a.y * w1.y + a.z * w2.y + a.w * w3.y;
;                     d2 += a.x * w0.z + a.y * w1.z + a.z * w2.z + a.w * w3.z;
;                     d3 += a.x * w0.w + a.y * w1.w + a.z * w2.w + a.w * w3.w;
;                 }
;             }
;             if (want_dt) {
;                 wave_sum4(d0, d1, d2, d3);
;                 if (lane == 0) *(f32x4*)(DT + (size_t)row * 4) = (f32x4){d0, d1, d2, d3};
;             }
	v_pk_fma_f32 v[88:89], v[166:167], v[130:131], v[88:89] op_sel_hi:[0,1,1]
	v_pk_add_f32 v[118:119], v[122:123], v[118:119]
	s_waitcnt lgkmcnt(4)
	v_pk_fma_f32 v[88:89], v[166:167], v[134:135], v[88:89] op_sel:[1,0,0]
	v_pk_fma_f32 v[86:87], v[86:87], v[124:125], v[150:151] op_sel:[1,0,0]
	v_pk_add_f32 v[88:89], v[118:119], v[88:89]
	s_waitcnt lgkmcnt(2)
	v_pk_mul_f32 v[118:119], v[102:103], v[138:139] op_sel:[1,0]
	v_pk_fma_f32 v[90:91], v[96:97], v[90:91], v[170:171] op_sel_hi:[0,1,1]
	v_pk_fma_f32 v[92:93], v[102:103], v[92:93], v[118:119] op_sel_hi:[0,1,1]
	s_waitcnt lgkmcnt(1)
	v_pk_fma_f32 v[92:93], v[112:113], v[154:155], v[92:93] op_sel_hi:[0,1,1]
	s_waitcnt lgkmcnt(0)
	v_pk_fma_f32 v[92:93], v[112:113], v[158:159], v[92:93] op_sel:[1,0,0]
	v_pk_add_f32 v[86:87], v[86:87], 0 op_sel_hi:[1,0]
	v_pk_add_f32 v[88:89], v[88:89], v[92:93]
	s_nop 1
	v_mov_b32_dpp v92, v88 quad_perm:[1,0,3,2] row_mask:0xf bank_mask:0xf
	v_mov_b32_dpp v93, v89 quad_perm:[1,0,3,2] row_mask:0xf bank_mask:0xf
	v_pk_fma_f32 v[90:91], v[166:167], v[132:133], v[90:91] op_sel_hi:[0,1,1]
	v_pk_fma_f32 v[90:91], v[166:167], v[136:137], v[90:91] op_sel:[1,0,0]
	s_waitcnt lgkmcnt(0)
	v_pk_add_f32 v[88:89], v[88:89], v[92:93]
	s_nop 1
	v_mov_b32_dpp v92, v88 quad_perm:[2,3,0,1] row_mask:0xf bank_mask:0xf
	v_mov_b32_dpp v93, v89 quad_perm:[2,3,0,1] row_mask:0xf bank_mask:0xf
	s_waitcnt lgkmcnt(0)
	v_pk_add_f32 v[88:89], v[88:89], v[92:93]
	s_nop 1
	v_mov_b32_dpp v92, v88 row_half_mirror row_mask:0xf bank_mask:0xf
	v_mov_b32_dpp v93, v89 row_half_mirror row_mask:0xf bank_mask:0xf
	s_waitcnt lgkmcnt(0)
	v_pk_add_f32 v[88:89], v[88:89], v[92:93]
	s_nop 1
	v_mov_b32_dpp v92, v88 row_mirror row_mask:0xf bank_mask:0xf
	v_mov_b32_dpp v93, v89 row_mirror row_mask:0xf bank_mask:0xf
	s_waitcnt lgkmcnt(0)
	v_pk_add_f32 v[88:89], v[88:89], v[92:93]
	v_mov_b32_e32 v92, v88
	v_mov_b32_e32 v93, v89
	s_nop 1
	v_permlane16_swap_b32_e32 v88, v92
	v_permlane16_swap_b32_e32 v89, v93
	s_waitcnt lgkmcnt(0)
	v_pk_add_f32 v[88:89], v[88:89], v[92:93]
	v_pk_fma_f32 v[92:93], v[162:163], v[120:121], v[106:107] op_sel_hi:[0,1,1]
	v_pk_fma_f32 v[92:93], v[162:163], v[128:129], v[92:93] op_sel:[1,0,0]
	s_nop 0
	v_pk_add_f32 v[86:87], v[86:87], v[92:93]
	s_nop 0
	v_pk_add_f32 v[86:87], v[86:87], v[90:91]
	v_pk_mul_f32 v[90:91], v[102:103], v[140:141] op_sel:[1,0]
	s_nop 0
	v_pk_fma_f32 v[90:91], v[102:103], v[94:95], v[90:91] op_sel_hi:[0,1,1]
	v_pk_fma_f32 v[90:91], v[112:113], v[156:157], v[90:91] op_sel_hi:[0,1,1]
	v_pk_fma_f32 v[90:91], v[112:113], v[160:161], v[90:91] op_sel:[1,0,0]
	s_nop 0
	v_pk_add_f32 v[86:87], v[86:87], v[90:91]
	s_nop 1
	v_mov_b32_dpp v90, v86 quad_perm:[1,0,3,2] row_mask:0xf bank_mask:0xf
	v_mov_b32_dpp v91, v87 quad_perm:[1,0,3,2] row_mask:0xf bank_mask:0xf
	s_waitcnt lgkmcnt(0)
	v_pk_add_f32 v[86:87], v[86:87], v[90:91]
	s_nop 1
	v_mov_b32_dpp v90, v86 quad_perm:[2,3,0,1] row_mask:0xf bank_mask:0xf
	v_mov_b32_dpp v91, v87 quad_perm:[2,3,0,1] row_mask:0xf bank_mask:0xf
	s_waitcnt lgkmcnt(0)
	v_pk_add_f32 v[86:87], v[86:87], v[90:91]
	s_nop 1
	v_mov_b32_dpp v90, v86 row_half_mirror row_mask:0xf bank_mask:0xf
	v_mov_b32_dpp v91, v87 row_half_mirror row_mask:0xf bank_mask:0xf
	s_waitcnt lgkmcnt(0)
	v_pk_add_f32 v[86:87], v[86:87], v[90:91]
	s_nop 1
	v_mov_b32_dpp v90, v86 row_mirror row_mask:0xf bank_mask:0xf
	v_mov_b32_dpp v91, v87 row_mirror row_mask:0xf bank_mask:0xf
	s_waitcnt lgkmcnt(0)
	v_pk_add_f32 v[86:87], v[86:87], v[90:91]
	v_mov_b32_e32 v90, v86
	v_mov_b32_e32 v91, v87
	s_nop 1
	v_permlane16_swap_b32_e32 v86, v90
	v_permlane16_swap_b32_e32 v87, v91
	s_waitcnt lgkmcnt(0)
	v_pk_add_f32 v[90:91], v[86:87], v[90:91]
	v_mov_b32_e32 v86, v88
	v_mov_b32_e32 v87, v89
	v_mov_b32_e32 v92, v90
	v_mov_b32_e32 v93, v91
	s_nop 1
	v_permlane32_swap_b32_e32 v88, v86
	v_permlane32_swap_b32_e32 v89, v87
	v_permlane32_swap_b32_e32 v90, v92
	v_permlane32_swap_b32_e32 v91, v93
	s_and_saveexec_b64 s[6:7], s[0:1]
	s_cbranch_execz .LBB0_203
	v_readlane_b32 s36, v253, 23
	v_readlane_b32 s38, v253, 25
	v_readlane_b32 s39, v253, 26
	s_waitcnt lgkmcnt(0)
	v_pk_add_f32 v[90:91], v[90:91], v[92:93]
	v_pk_add_f32 v[88:89], v[88:89], v[86:87]
	v_lshl_add_u64 v[94:95], s[38:39], 0, v[76:77]
	v_readlane_b32 s37, v253, 24
	global_store_dwordx4 v[94:95], v[88:91], off
	s_branch .LBB0_203

; DI void wave_sum2(float& a, float& b) {
; #pragma unroll
;     for (int o = 1; o < 64; o <<= 1) { const float ta = __shfl_xor(a, o), tb = __shfl_xor(b, o); a += ta; b += tb; }
; }
; DI void lnmod_phase(const Args& A, LAS unsigned char* lds, int tid, int bid, int G, bool init, int l_norm, int i_norm, int l_mod, int i_mod, bool want_dt, int nrows, bool ctx_partial, const float* gprev, const float* bprev) {
;     ...
;             float s = 0.f, s2 = 0.f;
; #pragma unroll
;             for (int j = 0; j < 4; ++j) { s += (v[j].x + v[j].y) + (v[j].z + v[j].w); s2 += (v[j].x * v[j].x + v[j].y * v[j].y) + (v[j].z * v[j].z + v[j].w * v[j].w); }
;             wave_sum2(s, s2);
;             const float mean = s * (1.f / DM);
;             const float rstd = 1.0f / sqrtf(fmaxf(s2 * (1.f / DM) - mean * mean, 0.f) + 1e-5f);
; #pragma unroll
;             for (int j = 0; j < 4; ++j) v[j] = v[j] - mean;
;             if (l_mod >= 0 && lane == 0) STAT[row] = (f32x2){mean, rstd};
.LBB0_233:
	s_or_b64 exec, exec, s[4:5]
	s_andn2_b64 vcc, exec, s[2:3]
	s_cbranch_vccnz .LBB0_237
	v_pk_add_f32 v[110:111], v[108:109], v[64:65]
	v_mul_f32_e32 v77, v65, v65
	v_add_f32_e32 v71, v110, v111
	v_add_f32_e32 v107, 0, v71
	v_mul_f32_e32 v71, v108, v108
	v_fmac_f32_e32 v71, v64, v64
	v_fmac_f32_e32 v77, v109, v109
	v_pk_add_f32 v[110:111], v[66:67], v[68:69]
	v_add_f32_e32 v71, v71, v77
	v_pk_add_f32 v[110:111], v[110:111], v[110:111] op_sel_hi:[0,1]
	v_mul_f32_e32 v77, v66, v66
	v_mul_f32_e32 v79, v69, v69
	v_fmac_f32_e32 v77, v68, v68
	v_fmac_f32_e32 v79, v67, v67
	v_mul_f32_e32 v110, v73, v73
	v_mul_f32_e32 v112, v75, v75
	v_add_f32_e32 v77, v77, v79
	v_fmac_f32_e32 v110, v72, v72
	v_fmac_f32_e32 v112, v74, v74
	v_add_f32_e32 v79, v71, v77
	v_add_f32_e32 v110, v110, v112
	v_add_f32_e32 v77, v72, v73
	v_add_f32_e32 v71, v74, v75
	v_add_f32_e32 v114, v110, v79
	v_mov_b32_e32 v79, v111
	v_pk_add_f32 v[112:113], v[76:77], v[70:71]
	v_pk_add_f32 v[110:111], v[78:79], v[106:107]
	v_mul_f32_e32 v77, v70, v70
	v_mul_f32_e32 v79, v106, v106
	v_fmac_f32_e32 v77, v76, v76
	v_fmac_f32_e32 v79, v78, v78
	v_add_f32_e32 v77, v77, v79
	v_and_b32_e32 v79, 64, v210
	v_add_u32_e32 v79, 64, v79
	v_xor_b32_e32 v107, 1, v210
	v_cmp_lt_i32_e32 vcc, v107, v79
	v_pk_add_f32 v[110:111], v[112:113], v[110:111]
	v_add_f32_e32 v77, v77, v114
	v_cndmask_b32_e32 v107, v210, v107, vcc
	v_add_f32_e32 v71, v110, v111
	v_lshlrev_b32_e32 v107, 2, v107
	s_nop 1
	v_mov_b32_dpp v110, v71 quad_perm:[1,0,3,2] row_mask:0xf bank_mask:0xf
	v_mov_b32_dpp v107, v77 quad_perm:[1,0,3,2] row_mask:0xf bank_mask:0xf
	s_mov_b32 s4, 0x3a800000
	s_waitcnt lgkmcnt(1)
	v_add_f32_e32 v71, v71, v110
	s_waitcnt lgkmcnt(0)
	v_add_f32_e32 v77, v77, v107
	v_xor_b32_e32 v107, 2, v210
	v_cmp_lt_i32_e32 vcc, v107, v79
	s_nop 1
	v_cndmask_b32_e32 v107, v210, v107, vcc
	v_lshlrev_b32_e32 v107, 2, v107
	s_nop 1
	v_mov_b32_dpp v110, v71 quad_perm:[2,3,0,1] row_mask:0xf bank_mask:0xf
	v_mov_b32_dpp v107, v77 quad_perm:[2,3,0,1] row_mask:0xf bank_mask:0xf
	s_waitcnt lgkmcnt(1)
	v_add_f32_e32 v71, v71, v110
	s_waitcnt lgkmcnt(0)
	v_add_f32_e32 v77, v77, v107
	v_xor_b32_e32 v107, 4, v210
	v_cmp_lt_i32_e32 vcc, v107, v79
	s_nop 1
	v_cndmask_b32_e32 v107, v210, v107, vcc
	v_lshlrev_b32_e32 v107, 2, v107
	s_nop 1
	v_mov_b32_dpp v110, v71 row_half_mirror row_mask:0xf bank_mask:0xf
	v_mov_b32_dpp v107, v77 row_half_mirror row_mask:0xf bank_mask:0xf
	s_waitcnt lgkmcnt(1)
	v_add_f32_e32 v71, v71, v110
	s_waitcnt lgkmcnt(0)
	v_add_f32_e32 v77, v77, v107
	v_xor_b32_e32 v107, 8, v210
	v_cmp_lt_i32_e32 vcc, v107, v79
	s_nop 1
	v_cndmask_b32_e32 v107, v210, v107, vcc
	v_lshlrev_b32_e32 v107, 2, v107
	s_nop 1
	v_mov_b32_dpp v110, v71 row_mirror row_mask:0xf bank_mask:0xf
	v_mov_b32_dpp v107, v77 row_mirror row_mask:0xf bank_mask:0xf
	s_waitcnt lgkmcnt(1)
	v_add_f32_e32 v71, v71, v110
	s_waitcnt lgkmcnt(0)
	v_add_f32_e32 v77, v77, v107
	v_xor_b32_e32 v107, 16, v210
	v_cmp_lt_i32_e32 vcc, v107, v79
	s_nop 1
	v_cndmask_b32_e32 v107, v210, v107, vcc
	v_lshlrev_b32_e32 v107, 2, v107
	v_mov_b32_e32 v110, v71
	v_mov_b32_e32 v107, v77
	s_nop 1
	v_permlane16_swap_b32_e32 v71, v110
	v_permlane16_swap_b32_e32 v77, v107
	s_waitcnt lgkmcnt(1)
	v_add_f32_e32 v71, v71, v110
	s_waitcnt lgkmcnt(0)
	v_add_f32_e32 v77, v77, v107
	v_xor_b32_e32 v107, 32, v210
	v_cmp_lt_i32_e32 vcc, v107, v79
	s_nop 1
	v_cndmask_b32_e32 v79, v210, v107, vcc
	v_lshlrev_b32_e32 v79, 2, v79
	v_mov_b32_e32 v107, v71
	v_mov_b32_e32 v79, v77
	s_nop 1
	v_permlane32_swap_b32_e32 v71, v107
	v_permlane32_swap_b32_e32 v77, v79
	s_waitcnt lgkmcnt(1)
	v_add_f32_e32 v71, v71, v107
	v_mul_f32_e32 v112, 0x3a800000, v71
	s_waitcnt lgkmcnt(0)
	v_add_f32_e32 v77, v77, v79
	v_mul_f32_e32 v71, v112, v112
	v_fma_f32 v71, v77, s4, -v71
	v_max_f32_e32 v71, 0, v71
	v_add_f32_e32 v71, 0x3727c5ac, v71
	v_mul_f32_e32 v77, 0x4f800000, v71
	v_cmp_gt_f32_e32 vcc, s65, v71
	s_nop 1
	v_cndmask_b32_e32 v71, v71, v77, vcc
	v_sqrt_f32_e32 v77, v71
	s_nop 0
	v_add_u32_e32 v79, -1, v77
	v_fma_f32 v107, -v79, v77, v71
	v_cmp_ge_f32_e64 s[4:5], 0, v107
	v_add_u32_e32 v107, 1, v77
	s_nop 0
	v_cndmask_b32_e64 v79, v77, v79, s[4:5]
	v_fma_f32 v77, -v107, v77, v71
	v_cmp_lt_f32_e64 s[4:5], 0, v77
	s_nop 1
	v_cndmask_b32_e64 v77, v79, v107, s[4:5]
	v_mul_f32_e32 v79, 0x37800000, v77
	v_cndmask_b32_e32 v77, v77, v79, vcc
	v_cmp_class_f32_e32 vcc, v71, v208
	s_nop 1
	v_cndmask_b32_e32 v71, v77, v71, vcc
	v_div_scale_f32 v77, s[4:5], v71, v71, 1.0
	v_rcp_f32_e32 v79, v77
	s_nop 0
	v_fma_f32 v107, -v77, v79, 1.0
	v_fmac_f32_e32 v79, v107, v79
	v_div_scale_f32 v107, vcc, 1.0, v71, 1.0
	v_mul_f32_e32 v110, v107, v79
	v_fma_f32 v111, -v77, v110, v107
	v_fmac_f32_e32 v110, v111, v79
	v_fma_f32 v77, -v77, v110, v107
	v_div_fmas_f32 v77, v77, v79, v110
	v_div_fixup_f32 v110, v77, v71, 1.0
	s_and_saveexec_b64 s[4:5], s[18:19]
	s_cbranch_execz .LBB0_236
	v_readlane_b32 s36, v253, 23
	v_readlane_b32 s38, v253, 25
	v_readlane_b32 s39, v253, 26
	v_mov_b32_e32 v113, v110
	v_readlane_b32 s37, v253, 24
	v_lshl_add_u64 v[114:115], s[38:39], 0, v[92:93]
	global_store_dwordx2 v[114:115], v[112:113], off

; DI void wave_sum2(float& a, float& b) {
; #pragma unroll
;     for (int o = 1; o < 64; o <<= 1) { const float ta = __shfl_xor(a, o), tb = __shfl_xor(b, o); a += ta; b += tb; }
; }
; DI void lnmod_phase(const Args& A, LAS unsigned char* lds, int tid, int bid, int G, bool init, int l_norm, int i_norm, int l_mod, int i_mod, bool want_dt, int nrows, bool ctx_partial, const float* gprev, const float* bprev) {
;     ...
;             float s = 0.f, s2 = 0.f;
; #pragma unroll
;             for (int j = 0; j < 4; ++j) { s += (v[j].x + v[j].y) + (v[j].z + v[j].w); s2 += (v[j].x * v[j].x + v[j].y * v[j].y) + (v[j].z * v[j].z + v[j].w * v[j].w); }
;             wave_sum2(s, s2);
;             const float mean = s * (1.f / DM);
;             const float rstd = 1.0f / sqrtf(fmaxf(s2 * (1.f / DM) - mean * mean, 0.f) + 1e-5f);
; #pragma unroll
;             for (int j = 0; j < 4; ++j) v[j] = v[j] - mean;
;             if (l_mod >= 0 && lane == 0) STAT[row] = (f32x2){mean, rstd};
.LBB0_284:
	s_or_b64 exec, exec, s[4:5]
	s_andn2_b64 vcc, exec, s[2:3]
	s_cbranch_vccnz .LBB0_279
	v_pk_add_f32 v[108:109], v[104:105], v[88:89]
	v_mul_f32_e32 v99, v89, v89
	v_add_f32_e32 v97, v108, v109
	v_add_f32_e32 v107, 0, v97
	v_mul_f32_e32 v97, v104, v104
	v_fmac_f32_e32 v97, v88, v88
	v_fmac_f32_e32 v99, v105, v105
	v_add_f32_e32 v97, v97, v99
	v_pk_add_f32 v[108:109], v[100:101], v[90:91]
	v_mul_f32_e32 v99, v100, v100
	v_mul_f32_e32 v103, v91, v91
	v_pk_add_f32 v[108:109], v[108:109], v[108:109] op_sel_hi:[0,1]
	v_fmac_f32_e32 v99, v90, v90
	v_fmac_f32_e32 v103, v101, v101
	v_add_f32_e32 v99, v99, v103
	v_mul_f32_e32 v108, v95, v95
	v_mul_f32_e32 v110, v93, v93
	v_add_f32_e32 v97, v97, v99
	v_add_f32_e32 v99, v94, v95
	v_add_f32_e32 v103, v92, v93
	v_fmac_f32_e32 v108, v94, v94
	v_fmac_f32_e32 v110, v92, v92
	v_add_f32_e32 v108, v108, v110
	v_pk_add_f32 v[110:111], v[98:99], v[102:103]
	v_mul_f32_e32 v99, v102, v102
	v_mul_f32_e32 v103, v106, v106
	v_fmac_f32_e32 v99, v98, v98
	v_fmac_f32_e32 v103, v96, v96
	v_add_f32_e32 v112, v108, v97
	v_mov_b32_e32 v97, v109
	v_add_f32_e32 v99, v99, v103
	v_and_b32_e32 v103, 64, v210
	v_pk_add_f32 v[108:109], v[96:97], v[106:107]
	v_add_u32_e32 v103, 64, v103
	v_xor_b32_e32 v107, 1, v210
	v_cmp_lt_i32_e32 vcc, v107, v103
	v_pk_add_f32 v[108:109], v[110:111], v[108:109]
	v_add_f32_e32 v99, v99, v112
	v_cndmask_b32_e32 v107, v210, v107, vcc
	v_add_f32_e32 v97, v108, v109
	v_lshlrev_b32_e32 v107, 2, v107
	s_nop 1
	v_mov_b32_dpp v108, v97 quad_perm:[1,0,3,2] row_mask:0xf bank_mask:0xf
	v_mov_b32_dpp v107, v99 quad_perm:[1,0,3,2] row_mask:0xf bank_mask:0xf
	s_mov_b32 s4, 0x3a800000
	s_waitcnt lgkmcnt(1)
	v_add_f32_e32 v97, v97, v108
	s_waitcnt lgkmcnt(0)
	v_add_f32_e32 v99, v99, v107
	v_xor_b32_e32 v107, 2, v210
	v_cmp_lt_i32_e32 vcc, v107, v103
	s_nop 1
	v_cndmask_b32_e32 v107, v210, v107, vcc
	v_lshlrev_b32_e32 v107, 2, v107
	s_nop 1
	v_mov_b32_dpp v108, v97 quad_perm:[2,3,0,1] row_mask:0xf bank_mask:0xf
	v_mov_b32_dpp v107, v99 quad_perm:[2,3,0,1] row_mask:0xf bank_mask:0xf
	s_waitcnt lgkmcnt(1)
	v_add_f32_e32 v97, v97, v108
	s_waitcnt lgkmcnt(0)
	v_add_f32_e32 v99, v99, v107
	v_xor_b32_e32 v107, 4, v210
	v_cmp_lt_i32_e32 vcc, v107, v103
	s_nop 1
	v_cndmask_b32_e32 v107, v210, v107, vcc
	v_lshlrev_b32_e32 v107, 2, v107
	s_nop 1
	v_mov_b32_dpp v108, v97 row_half_mirror row_mask:0xf bank_mask:0xf
	v_mov_b32_dpp v107, v99 row_half_mirror row_mask:0xf bank_mask:0xf
	s_waitcnt lgkmcnt(1)
	v_add_f32_e32 v97, v97, v108
	s_waitcnt lgkmcnt(0)
	v_add_f32_e32 v99, v99, v107
	v_xor_b32_e32 v107, 8, v210
	v_cmp_lt_i32_e32 vcc, v107, v103
	s_nop 1
	v_cndmask_b32_e32 v107, v210, v107, vcc
	v_lshlrev_b32_e32 v107, 2, v107
	s_nop 1
	v_mov_b32_dpp v108, v97 row_mirror row_mask:0xf bank_mask:0xf
	v_mov_b32_dpp v107, v99 row_mirror row_mask:0xf bank_mask:0xf
	s_waitcnt lgkmcnt(1)
	v_add_f32_e32 v97, v97, v108
	s_waitcnt lgkmcnt(0)
	v_add_f32_e32 v99, v99, v107
	v_xor_b32_e32 v107, 16, v210
	v_cmp_lt_i32_e32 vcc, v107, v103
	s_nop 1
	v_cndmask_b32_e32 v107, v210, v107, vcc
	v_lshlrev_b32_e32 v107, 2, v107
	v_mov_b32_e32 v108, v97
	v_mov_b32_e32 v107, v99
	s_nop 1
	v_permlane16_swap_b32_e32 v97, v108
	v_permlane16_swap_b32_e32 v99, v107
	s_waitcnt lgkmcnt(1)
	v_add_f32_e32 v97, v97, v108
	s_waitcnt lgkmcnt(0)
	v_add_f32_e32 v99, v99, v107
	v_xor_b32_e32 v107, 32, v210
	v_cmp_lt_i32_e32 vcc, v107, v103
	s_nop 1
	v_cndmask_b32_e32 v103, v210, v107, vcc
	v_lshlrev_b32_e32 v103, 2, v103
	v_mov_b32_e32 v107, v97
	v_mov_b32_e32 v103, v99
	s_nop 1
	v_permlane32_swap_b32_e32 v97, v107
	v_permlane32_swap_b32_e32 v99, v103
	s_waitcnt lgkmcnt(1)
	v_add_f32_e32 v97, v97, v107
	v_mul_f32_e32 v110, 0x3a800000, v97
	s_waitcnt lgkmcnt(0)
	v_add_f32_e32 v99, v99, v103
	v_mul_f32_e32 v97, v110, v110
	v_fma_f32 v97, v99, s4, -v97
	v_max_f32_e32 v97, 0, v97
	v_add_f32_e32 v97, 0x3727c5ac, v97
	v_mul_f32_e32 v99, 0x4f800000, v97
	v_cmp_gt_f32_e32 vcc, s65, v97
	s_nop 1
	v_cndmask_b32_e32 v97, v97, v99, vcc
	v_sqrt_f32_e32 v99, v97
	s_nop 0
	v_add_u32_e32 v103, -1, v99
	v_fma_f32 v107, -v103, v99, v97
	v_cmp_ge_f32_e64 s[4:5], 0, v107
	v_add_u32_e32 v107, 1, v99
	s_nop 0
	v_cndmask_b32_e64 v103, v99, v103, s[4:5]
	v_fma_f32 v99, -v107, v99, v97
	v_cmp_lt_f32_e64 s[4:5], 0, v99
	s_nop 1
	v_cndmask_b32_e64 v99, v103, v107, s[4:5]
	v_mul_f32_e32 v103, 0x37800000, v99
	v_cndmask_b32_e32 v99, v99, v103, vcc
	v_cmp_class_f32_e32 vcc, v97, v208
	s_nop 1
	v_cndmask_b32_e32 v97, v99, v97, vcc
	v_div_scale_f32 v99, s[4:5], v97, v97, 1.0
	v_rcp_f32_e32 v103, v99
	s_nop 0
	v_fma_f32 v107, -v99, v103, 1.0
	v_fmac_f32_e32 v103, v107, v103
	v_div_scale_f32 v107, vcc, 1.0, v97, 1.0
	v_mul_f32_e32 v108, v107, v103
	v_fma_f32 v109, -v99, v108, v107
	v_fmac_f32_e32 v108, v109, v103
	v_fma_f32 v99, -v99, v108, v107
	v_div_fmas_f32 v99, v99, v103, v108
	v_div_fixup_f32 v108, v99, v97, 1.0
	s_and_saveexec_b64 s[4:5], s[14:15]
	s_cbranch_execz .LBB0_287
	v_readlane_b32 s24, v253, 23
	v_readlane_b32 s26, v253, 25
	v_readlane_b32 s27, v253, 26
	v_mov_b32_e32 v111, v108
	v_readlane_b32 s25, v253, 24
	v_lshl_add_u64 v[112:113], s[26:27], 0, v[74:75]
	global_store_dwordx2 v[112:113], v[110:111], off
